# EpiMerge (P10a/b): second gate/M1 loads of each row-group issued with the first (renamed dests, counted vmcnt)
# baseline (speedup 1.0000x reference)
; __device__ __forceinline__ u32x4 pack8(f32x4 a, f32x4 b) { u32x4 w; w.x = pk2(a[0], a[1]); w.y = pk2(a[2], a[3]); w.z = pk2(b[0], b[1]); w.w = pk2(b[2], b[3]); return w; }
;     __device__ __forceinline__ void operator()(AccRef acc, const Unit& u, int wr, int wc, int fr, int fq) const {
;     ...
;             _Pragma("unroll") for (int bj = 0; bj < 2; ++bj) { const int col = col0 + bj * 128;
;                 const u32x2 gw = *(const u32x2*)(ZG8 + (size_t)row * 2048 + WHICH * 1024 + col);
;                 f32x4 v[2];
;                 _Pragma("unroll") for (int n = 0; n < 2; ++n) _Pragma("unroll") for (int i = 0; i < 4; ++i) v[n][i] = acc[ai][bj][m][n][i] * ((float)((gw[n] >> (8 * i)) & 255u) * (1.f / 255.f));
;                 if (WHICH == 0) *(u32x4*)(M1 + (size_t)row * 1024 + col) = pack8(v[0], v[1]);
.LBB0_1278:
	v_lshl_add_u32 v142, s56, 8, v147
	v_ashrrev_i32_e32 v143, 31, v142
	v_lshl_or_b32 v134, s54, 8, v148
	v_lshlrev_b64 v[136:137], 11, v[142:143]
	v_lshl_add_u64 v[138:139], s[22:23], 0, v[136:137]
	v_ashrrev_i32_e32 v135, 31, v134
	v_lshl_add_u64 v[154:155], v[138:139], 0, v[134:135]
	global_load_dwordx2 v[156:157], v[154:155], off
	global_load_dwordx2 v[200:201], v[154:155], off offset:128
	v_lshlrev_b64 v[138:139], 1, v[134:135]
	v_lshl_add_u64 v[158:159], s[20:21], 0, v[136:137]
	v_lshl_add_u64 v[158:159], v[158:159], 0, v[138:139]
	s_waitcnt vmcnt(1)
	v_cvt_f32_ubyte1_e32 v161, v156
	v_cvt_f32_ubyte0_e32 v160, v156
	v_cvt_f32_ubyte3_e32 v163, v156
	v_cvt_f32_ubyte2_e32 v162, v156
	v_cvt_f32_ubyte1_e32 v165, v157
	v_cvt_f32_ubyte0_e32 v164, v157
	v_cvt_f32_ubyte3_e32 v167, v157
	v_cvt_f32_ubyte2_e32 v166, v157
	v_pk_mul_f32 v[156:157], v[160:161], s[10:11] op_sel_hi:[1,0]
	v_pk_mul_f32 v[160:161], v[162:163], s[10:11] op_sel_hi:[1,0]
	v_pk_mul_f32 v[162:163], v[164:165], s[10:11] op_sel_hi:[1,0]
	v_pk_mul_f32 v[164:165], v[166:167], s[10:11] op_sel_hi:[1,0]
	v_pk_mul_f32 v[126:127], v[126:127], v[156:157]
	v_pk_mul_f32 v[128:129], v[128:129], v[160:161]
	v_pk_mul_f32 v[156:157], v[122:123], v[162:163]
	v_pk_mul_f32 v[160:161], v[124:125], v[164:165]
	v_cvt_pk_bf16_f32 v122, v126, v127
	v_cvt_pk_bf16_f32 v123, v128, v129
	v_cvt_pk_bf16_f32 v124, v156, v157
	v_cvt_pk_bf16_f32 v125, v160, v161
	global_store_dwordx4 v[158:159], v[122:125], off
	s_nop 0
	s_waitcnt vmcnt(1)
	v_cvt_f32_ubyte3_e32 v127, v200
	v_cvt_f32_ubyte1_e32 v125, v200
	v_cvt_f32_ubyte0_e32 v124, v200
	v_cvt_f32_ubyte2_e32 v126, v200
	v_cvt_f32_ubyte1_e32 v129, v201
	v_cvt_f32_ubyte0_e32 v128, v201
	v_cvt_f32_ubyte3_e32 v155, v201
	v_cvt_f32_ubyte2_e32 v154, v201
	v_pk_mul_f32 v[122:123], v[124:125], s[10:11] op_sel_hi:[1,0]
	v_pk_mul_f32 v[124:125], v[126:127], s[10:11] op_sel_hi:[1,0]
	v_pk_mul_f32 v[126:127], v[128:129], s[10:11] op_sel_hi:[1,0]
	v_pk_mul_f32 v[128:129], v[154:155], s[10:11] op_sel_hi:[1,0]
	v_pk_mul_f32 v[118:119], v[118:119], v[122:123]
	v_pk_mul_f32 v[120:121], v[120:121], v[124:125]
	v_pk_mul_f32 v[122:123], v[114:115], v[126:127]
	v_pk_mul_f32 v[124:125], v[116:117], v[128:129]
	v_cvt_pk_bf16_f32 v114, v118, v119
	v_cvt_pk_bf16_f32 v115, v120, v121
	v_cvt_pk_bf16_f32 v116, v122, v123
	v_cvt_pk_bf16_f32 v117, v124, v125
	global_store_dwordx4 v[158:159], v[114:117], off offset:256
	s_nop 1
	v_or_b32_e32 v114, 16, v142
	v_ashrrev_i32_e32 v115, 31, v114
	v_lshlrev_b64 v[114:115], 11, v[114:115]
	v_lshl_add_u64 v[116:117], s[22:23], 0, v[114:115]
	v_lshl_add_u64 v[116:117], v[116:117], 0, v[134:135]
	global_load_dwordx2 v[118:119], v[116:117], off
	global_load_dwordx2 v[200:201], v[116:117], off offset:128
	v_lshl_add_u64 v[114:115], s[20:21], 0, v[114:115]
	v_lshl_add_u64 v[114:115], v[114:115], 0, v[138:139]
	s_waitcnt vmcnt(1)
	v_cvt_f32_ubyte1_e32 v121, v118
	v_cvt_f32_ubyte0_e32 v120, v118
	v_cvt_f32_ubyte3_e32 v123, v118
	v_cvt_f32_ubyte2_e32 v122, v118
	v_cvt_f32_ubyte1_e32 v125, v119
	v_cvt_f32_ubyte0_e32 v124, v119
	v_cvt_f32_ubyte3_e32 v127, v119
	v_cvt_f32_ubyte2_e32 v126, v119
	v_pk_mul_f32 v[118:119], v[120:121], s[10:11] op_sel_hi:[1,0]
	v_pk_mul_f32 v[120:121], v[122:123], s[10:11] op_sel_hi:[1,0]
	v_pk_mul_f32 v[122:123], v[124:125], s[10:11] op_sel_hi:[1,0]
	v_pk_mul_f32 v[124:125], v[126:127], s[10:11] op_sel_hi:[1,0]
	v_pk_mul_f32 v[110:111], v[110:111], v[118:119]
	v_pk_mul_f32 v[112:113], v[112:113], v[120:121]
	v_pk_mul_f32 v[118:119], v[106:107], v[122:123]
	v_pk_mul_f32 v[120:121], v[108:109], v[124:125]
	v_cvt_pk_bf16_f32 v106, v110, v111
	v_cvt_pk_bf16_f32 v107, v112, v113
	v_cvt_pk_bf16_f32 v108, v118, v119
	v_cvt_pk_bf16_f32 v109, v120, v121
	global_store_dwordx4 v[114:115], v[106:109], off
	s_nop 0
	s_waitcnt vmcnt(1)
	v_cvt_f32_ubyte3_e32 v111, v200
	v_cvt_f32_ubyte1_e32 v109, v200
	v_cvt_f32_ubyte0_e32 v108, v200
	v_cvt_f32_ubyte2_e32 v110, v200
	v_cvt_f32_ubyte1_e32 v113, v201
	v_cvt_f32_ubyte0_e32 v112, v201
	v_cvt_f32_ubyte3_e32 v117, v201
	v_cvt_f32_ubyte2_e32 v116, v201
	v_pk_mul_f32 v[106:107], v[108:109], s[10:11] op_sel_hi:[1,0]
	v_pk_mul_f32 v[108:109], v[110:111], s[10:11] op_sel_hi:[1,0]
	v_pk_mul_f32 v[110:111], v[112:113], s[10:11] op_sel_hi:[1,0]
	v_pk_mul_f32 v[112:113], v[116:117], s[10:11] op_sel_hi:[1,0]
	v_pk_mul_f32 v[102:103], v[102:103], v[106:107]
	v_pk_mul_f32 v[104:105], v[104:105], v[108:109]
	v_pk_mul_f32 v[106:107], v[98:99], v[110:111]
	v_pk_mul_f32 v[108:109], v[100:101], v[112:113]
	v_cvt_pk_bf16_f32 v98, v102, v103
	v_cvt_pk_bf16_f32 v99, v104, v105
	v_cvt_pk_bf16_f32 v100, v106, v107
	v_cvt_pk_bf16_f32 v101, v108, v109
	global_store_dwordx4 v[114:115], v[98:101], off offset:256
	s_nop 1
	v_or_b32_e32 v98, 32, v142
	v_ashrrev_i32_e32 v99, 31, v98
	v_lshlrev_b64 v[98:99], 11, v[98:99]
	v_lshl_add_u64 v[100:101], s[22:23], 0, v[98:99]
	v_lshl_add_u64 v[100:101], v[100:101], 0, v[134:135]
	global_load_dwordx2 v[102:103], v[100:101], off
	global_load_dwordx2 v[200:201], v[100:101], off offset:128
	v_lshl_add_u64 v[98:99], s[20:21], 0, v[98:99]
	v_lshl_add_u64 v[98:99], v[98:99], 0, v[138:139]
	s_waitcnt vmcnt(1)
	v_cvt_f32_ubyte1_e32 v105, v102
	v_cvt_f32_ubyte0_e32 v104, v102
	v_cvt_f32_ubyte3_e32 v107, v102
	v_cvt_f32_ubyte2_e32 v106, v102
	v_cvt_f32_ubyte1_e32 v109, v103
	v_cvt_f32_ubyte0_e32 v108, v103
	v_cvt_f32_ubyte3_e32 v111, v103
	v_cvt_f32_ubyte2_e32 v110, v103
	v_pk_mul_f32 v[102:103], v[104:105], s[10:11] op_sel_hi:[1,0]
	v_pk_mul_f32 v[104:105], v[106:107], s[10:11] op_sel_hi:[1,0]
	v_pk_mul_f32 v[106:107], v[108:109], s[10:11] op_sel_hi:[1,0]
	v_pk_mul_f32 v[108:109], v[110:111], s[10:11] op_sel_hi:[1,0]
	v_pk_mul_f32 v[94:95], v[94:95], v[102:103]
	v_pk_mul_f32 v[96:97], v[96:97], v[104:105]
	v_pk_mul_f32 v[102:103], v[90:91], v[106:107]
	v_pk_mul_f32 v[104:105], v[92:93], v[108:109]
	v_cvt_pk_bf16_f32 v90, v94, v95
	v_cvt_pk_bf16_f32 v91, v96, v97
	v_cvt_pk_bf16_f32 v92, v102, v103
	v_cvt_pk_bf16_f32 v93, v104, v105
	global_store_dwordx4 v[98:99], v[90:93], off
	s_nop 0
	s_waitcnt vmcnt(1)
; __device__ __forceinline__ u32x4 pack8(f32x4 a, f32x4 b) { u32x4 w; w.x = pk2(a[0], a[1]); w.y = pk2(a[2], a[3]); w.z = pk2(b[0], b[1]); w.w = pk2(b[2], b[3]); return w; }
;     __device__ __forceinline__ void operator()(AccRef acc, const Unit& u, int wr, int wc, int fr, int fq) const {
;     ...
;             _Pragma("unroll") for (int bj = 0; bj < 2; ++bj) { const int col = col0 + bj * 128;
;                 const u32x2 gw = *(const u32x2*)(ZG8 + (size_t)row * 2048 + WHICH * 1024 + col);
;                 f32x4 v[2];
;                 _Pragma("unroll") for (int n = 0; n < 2; ++n) _Pragma("unroll") for (int i = 0; i < 4; ++i) v[n][i] = acc[ai][bj][m][n][i] * ((float)((gw[n] >> (8 * i)) & 255u) * (1.f / 255.f));
;                 if (WHICH == 0) *(u32x4*)(M1 + (size_t)row * 1024 + col) = pack8(v[0], v[1]);
	v_cvt_f32_ubyte3_e32 v95, v200
	v_cvt_f32_ubyte1_e32 v93, v200
	v_cvt_f32_ubyte0_e32 v92, v200
	v_cvt_f32_ubyte2_e32 v94, v200
	v_cvt_f32_ubyte1_e32 v97, v201
	v_cvt_f32_ubyte0_e32 v96, v201
	v_cvt_f32_ubyte3_e32 v101, v201
	v_cvt_f32_ubyte2_e32 v100, v201
	v_pk_mul_f32 v[90:91], v[92:93], s[10:11] op_sel_hi:[1,0]
	v_pk_mul_f32 v[92:93], v[94:95], s[10:11] op_sel_hi:[1,0]
	v_pk_mul_f32 v[94:95], v[96:97], s[10:11] op_sel_hi:[1,0]
	v_pk_mul_f32 v[96:97], v[100:101], s[10:11] op_sel_hi:[1,0]
	v_pk_mul_f32 v[86:87], v[86:87], v[90:91]
	v_pk_mul_f32 v[88:89], v[88:89], v[92:93]
	v_pk_mul_f32 v[90:91], v[82:83], v[94:95]
	v_pk_mul_f32 v[92:93], v[84:85], v[96:97]
	v_cvt_pk_bf16_f32 v82, v86, v87
	v_cvt_pk_bf16_f32 v83, v88, v89
	v_cvt_pk_bf16_f32 v84, v90, v91
	v_cvt_pk_bf16_f32 v85, v92, v93
	global_store_dwordx4 v[98:99], v[82:85], off offset:256
	s_nop 1
	v_or_b32_e32 v82, 48, v142
	v_ashrrev_i32_e32 v83, 31, v82
	v_lshlrev_b64 v[82:83], 11, v[82:83]
	v_lshl_add_u64 v[84:85], s[22:23], 0, v[82:83]
	v_lshl_add_u64 v[84:85], v[84:85], 0, v[134:135]
	global_load_dwordx2 v[86:87], v[84:85], off
	global_load_dwordx2 v[200:201], v[84:85], off offset:128
	v_lshl_add_u64 v[82:83], s[20:21], 0, v[82:83]
	v_lshl_add_u64 v[82:83], v[82:83], 0, v[138:139]
	s_waitcnt vmcnt(1)
	v_cvt_f32_ubyte1_e32 v89, v86
	v_cvt_f32_ubyte0_e32 v88, v86
	v_cvt_f32_ubyte3_e32 v91, v86
	v_cvt_f32_ubyte2_e32 v90, v86
	v_cvt_f32_ubyte1_e32 v93, v87
	v_cvt_f32_ubyte0_e32 v92, v87
	v_cvt_f32_ubyte3_e32 v95, v87
	v_cvt_f32_ubyte2_e32 v94, v87
	v_pk_mul_f32 v[86:87], v[88:89], s[10:11] op_sel_hi:[1,0]
	v_pk_mul_f32 v[88:89], v[90:91], s[10:11] op_sel_hi:[1,0]
	v_pk_mul_f32 v[90:91], v[92:93], s[10:11] op_sel_hi:[1,0]
	v_pk_mul_f32 v[92:93], v[94:95], s[10:11] op_sel_hi:[1,0]
	v_pk_mul_f32 v[78:79], v[78:79], v[86:87]
	v_pk_mul_f32 v[80:81], v[80:81], v[88:89]
	v_pk_mul_f32 v[86:87], v[74:75], v[90:91]
	v_pk_mul_f32 v[88:89], v[76:77], v[92:93]
	v_cvt_pk_bf16_f32 v74, v78, v79
	v_cvt_pk_bf16_f32 v75, v80, v81
	v_cvt_pk_bf16_f32 v76, v86, v87
	v_cvt_pk_bf16_f32 v77, v88, v89
	global_store_dwordx4 v[82:83], v[74:77], off
	s_nop 0
	s_waitcnt vmcnt(1)
	v_cvt_f32_ubyte3_e32 v79, v200
	v_cvt_f32_ubyte1_e32 v77, v200
	v_cvt_f32_ubyte0_e32 v76, v200
	v_cvt_f32_ubyte2_e32 v78, v200
	v_cvt_f32_ubyte1_e32 v81, v201
	v_cvt_f32_ubyte0_e32 v80, v201
	v_cvt_f32_ubyte3_e32 v85, v201
	v_cvt_f32_ubyte2_e32 v84, v201
	v_pk_mul_f32 v[74:75], v[76:77], s[10:11] op_sel_hi:[1,0]
	v_pk_mul_f32 v[76:77], v[78:79], s[10:11] op_sel_hi:[1,0]
	v_pk_mul_f32 v[78:79], v[80:81], s[10:11] op_sel_hi:[1,0]
	v_pk_mul_f32 v[80:81], v[84:85], s[10:11] op_sel_hi:[1,0]
	v_pk_mul_f32 v[70:71], v[70:71], v[74:75]
	v_pk_mul_f32 v[72:73], v[72:73], v[76:77]
	v_pk_mul_f32 v[74:75], v[66:67], v[78:79]
	v_pk_mul_f32 v[76:77], v[68:69], v[80:81]
	v_cvt_pk_bf16_f32 v66, v70, v71
	v_cvt_pk_bf16_f32 v67, v72, v73
	v_cvt_pk_bf16_f32 v68, v74, v75
	v_cvt_pk_bf16_f32 v69, v76, v77
	global_store_dwordx4 v[82:83], v[66:69], off offset:256
	s_nop 1
	v_lshl_add_u64 v[66:67], v[136:137], 0, s[12:13]
	v_lshl_add_u64 v[68:69], s[22:23], 0, v[66:67]
	v_lshl_add_u64 v[68:69], v[68:69], 0, v[134:135]
	global_load_dwordx2 v[70:71], v[68:69], off
	global_load_dwordx2 v[200:201], v[68:69], off offset:128
	v_lshl_add_u64 v[66:67], s[20:21], 0, v[66:67]
	v_lshl_add_u64 v[66:67], v[66:67], 0, v[138:139]
	s_waitcnt vmcnt(1)
	v_cvt_f32_ubyte1_e32 v73, v70
	v_cvt_f32_ubyte0_e32 v72, v70
	v_cvt_f32_ubyte3_e32 v75, v70
	v_cvt_f32_ubyte2_e32 v74, v70
	v_cvt_f32_ubyte1_e32 v77, v71
	v_cvt_f32_ubyte0_e32 v76, v71
	v_cvt_f32_ubyte3_e32 v79, v71
	v_cvt_f32_ubyte2_e32 v78, v71
	v_pk_mul_f32 v[70:71], v[72:73], s[10:11] op_sel_hi:[1,0]
	v_pk_mul_f32 v[72:73], v[74:75], s[10:11] op_sel_hi:[1,0]
	v_pk_mul_f32 v[74:75], v[76:77], s[10:11] op_sel_hi:[1,0]
	v_pk_mul_f32 v[76:77], v[78:79], s[10:11] op_sel_hi:[1,0]
	v_pk_mul_f32 v[62:63], v[62:63], v[70:71]
	v_pk_mul_f32 v[64:65], v[64:65], v[72:73]
	v_pk_mul_f32 v[70:71], v[58:59], v[74:75]
	v_pk_mul_f32 v[72:73], v[60:61], v[76:77]
	v_cvt_pk_bf16_f32 v58, v62, v63
	v_cvt_pk_bf16_f32 v59, v64, v65
	v_cvt_pk_bf16_f32 v60, v70, v71
	v_cvt_pk_bf16_f32 v61, v72, v73
	global_store_dwordx4 v[66:67], v[58:61], off
	s_nop 0
	s_waitcnt vmcnt(1)
	v_cvt_f32_ubyte3_e32 v63, v200
	v_cvt_f32_ubyte1_e32 v61, v200
	v_cvt_f32_ubyte0_e32 v60, v200
	v_cvt_f32_ubyte2_e32 v62, v200
	v_cvt_f32_ubyte1_e32 v65, v201
	v_cvt_f32_ubyte0_e32 v64, v201
	v_cvt_f32_ubyte3_e32 v69, v201
	v_cvt_f32_ubyte2_e32 v68, v201
	v_pk_mul_f32 v[58:59], v[60:61], s[10:11] op_sel_hi:[1,0]
	v_pk_mul_f32 v[60:61], v[62:63], s[10:11] op_sel_hi:[1,0]
	v_pk_mul_f32 v[62:63], v[64:65], s[10:11] op_sel_hi:[1,0]
	v_pk_mul_f32 v[64:65], v[68:69], s[10:11] op_sel_hi:[1,0]
	v_pk_mul_f32 v[54:55], v[54:55], v[58:59]
	v_pk_mul_f32 v[56:57], v[56:57], v[60:61]
	v_pk_mul_f32 v[58:59], v[50:51], v[62:63]
	v_pk_mul_f32 v[60:61], v[52:53], v[64:65]
	v_cvt_pk_bf16_f32 v50, v54, v55
	v_cvt_pk_bf16_f32 v51, v56, v57
	v_cvt_pk_bf16_f32 v52, v58, v59
	v_cvt_pk_bf16_f32 v53, v60, v61
	global_store_dwordx4 v[66:67], v[50:53], off offset:256
	s_nop 1
	v_lshl_add_u64 v[50:51], v[136:137], 0, s[38:39]
	v_lshl_add_u64 v[52:53], s[22:23], 0, v[50:51]
	v_lshl_add_u64 v[52:53], v[52:53], 0, v[134:135]
	global_load_dwordx2 v[54:55], v[52:53], off
	global_load_dwordx2 v[200:201], v[52:53], off offset:128
	v_lshl_add_u64 v[50:51], s[20:21], 0, v[50:51]
	v_lshl_add_u64 v[50:51], v[50:51], 0, v[138:139]
	s_waitcnt vmcnt(1)
; __device__ __forceinline__ u32x4 pack8(f32x4 a, f32x4 b) { u32x4 w; w.x = pk2(a[0], a[1]); w.y = pk2(a[2], a[3]); w.z = pk2(b[0], b[1]); w.w = pk2(b[2], b[3]); return w; }
;     __device__ __forceinline__ void operator()(AccRef acc, const Unit& u, int wr, int wc, int fr, int fq) const {
;     ...
;             _Pragma("unroll") for (int bj = 0; bj < 2; ++bj) { const int col = col0 + bj * 128;
;                 const u32x2 gw = *(const u32x2*)(ZG8 + (size_t)row * 2048 + WHICH * 1024 + col);
;                 f32x4 v[2];
;                 _Pragma("unroll") for (int n = 0; n < 2; ++n) _Pragma("unroll") for (int i = 0; i < 4; ++i) v[n][i] = acc[ai][bj][m][n][i] * ((float)((gw[n] >> (8 * i)) & 255u) * (1.f / 255.f));
;                 if (WHICH == 0) *(u32x4*)(M1 + (size_t)row * 1024 + col) = pack8(v[0], v[1]);
	v_cvt_f32_ubyte1_e32 v57, v54
	v_cvt_f32_ubyte0_e32 v56, v54
	v_cvt_f32_ubyte3_e32 v59, v54
	v_cvt_f32_ubyte2_e32 v58, v54
	v_cvt_f32_ubyte1_e32 v61, v55
	v_cvt_f32_ubyte0_e32 v60, v55
	v_cvt_f32_ubyte3_e32 v63, v55
	v_cvt_f32_ubyte2_e32 v62, v55
	v_pk_mul_f32 v[54:55], v[56:57], s[10:11] op_sel_hi:[1,0]
	v_pk_mul_f32 v[56:57], v[58:59], s[10:11] op_sel_hi:[1,0]
	v_pk_mul_f32 v[58:59], v[60:61], s[10:11] op_sel_hi:[1,0]
	v_pk_mul_f32 v[60:61], v[62:63], s[10:11] op_sel_hi:[1,0]
	v_pk_mul_f32 v[46:47], v[46:47], v[54:55]
	v_pk_mul_f32 v[48:49], v[48:49], v[56:57]
	v_pk_mul_f32 v[54:55], v[42:43], v[58:59]
	v_pk_mul_f32 v[56:57], v[44:45], v[60:61]
	v_cvt_pk_bf16_f32 v42, v46, v47
	v_cvt_pk_bf16_f32 v43, v48, v49
	v_cvt_pk_bf16_f32 v44, v54, v55
	v_cvt_pk_bf16_f32 v45, v56, v57
	global_store_dwordx4 v[50:51], v[42:45], off
	s_nop 0
	s_waitcnt vmcnt(1)
	v_cvt_f32_ubyte3_e32 v47, v200
	v_cvt_f32_ubyte1_e32 v45, v200
	v_cvt_f32_ubyte0_e32 v44, v200
	v_cvt_f32_ubyte2_e32 v46, v200
	v_cvt_f32_ubyte1_e32 v49, v201
	v_cvt_f32_ubyte0_e32 v48, v201
	v_cvt_f32_ubyte3_e32 v53, v201
	v_cvt_f32_ubyte2_e32 v52, v201
	v_pk_mul_f32 v[42:43], v[44:45], s[10:11] op_sel_hi:[1,0]
	v_pk_mul_f32 v[44:45], v[46:47], s[10:11] op_sel_hi:[1,0]
	v_pk_mul_f32 v[46:47], v[48:49], s[10:11] op_sel_hi:[1,0]
	v_pk_mul_f32 v[48:49], v[52:53], s[10:11] op_sel_hi:[1,0]
	v_pk_mul_f32 v[38:39], v[38:39], v[42:43]
	v_pk_mul_f32 v[40:41], v[40:41], v[44:45]
	v_pk_mul_f32 v[42:43], v[34:35], v[46:47]
	v_pk_mul_f32 v[44:45], v[36:37], v[48:49]
	v_cvt_pk_bf16_f32 v34, v38, v39
	v_cvt_pk_bf16_f32 v35, v40, v41
	v_cvt_pk_bf16_f32 v36, v42, v43
	v_cvt_pk_bf16_f32 v37, v44, v45
	global_store_dwordx4 v[50:51], v[34:37], off offset:256
	s_nop 1
	v_lshl_add_u64 v[34:35], v[136:137], 0, s[42:43]
	v_lshl_add_u64 v[36:37], s[22:23], 0, v[34:35]
	v_lshl_add_u64 v[36:37], v[36:37], 0, v[134:135]
	global_load_dwordx2 v[38:39], v[36:37], off
	global_load_dwordx2 v[200:201], v[36:37], off offset:128
	v_lshl_add_u64 v[34:35], s[20:21], 0, v[34:35]
	v_lshl_add_u64 v[34:35], v[34:35], 0, v[138:139]
	s_waitcnt vmcnt(1)
	v_cvt_f32_ubyte1_e32 v41, v38
	v_cvt_f32_ubyte0_e32 v40, v38
	v_cvt_f32_ubyte3_e32 v43, v38
	v_cvt_f32_ubyte2_e32 v42, v38
	v_cvt_f32_ubyte1_e32 v45, v39
	v_cvt_f32_ubyte0_e32 v44, v39
	v_cvt_f32_ubyte3_e32 v47, v39
	v_cvt_f32_ubyte2_e32 v46, v39
	v_pk_mul_f32 v[38:39], v[40:41], s[10:11] op_sel_hi:[1,0]
	v_pk_mul_f32 v[40:41], v[42:43], s[10:11] op_sel_hi:[1,0]
	v_pk_mul_f32 v[42:43], v[44:45], s[10:11] op_sel_hi:[1,0]
	v_pk_mul_f32 v[44:45], v[46:47], s[10:11] op_sel_hi:[1,0]
	v_pk_mul_f32 v[30:31], v[30:31], v[38:39]
	v_pk_mul_f32 v[32:33], v[32:33], v[40:41]
	v_pk_mul_f32 v[38:39], v[26:27], v[42:43]
	v_pk_mul_f32 v[40:41], v[28:29], v[44:45]
	v_cvt_pk_bf16_f32 v26, v30, v31
	v_cvt_pk_bf16_f32 v27, v32, v33
	v_cvt_pk_bf16_f32 v28, v38, v39
	v_cvt_pk_bf16_f32 v29, v40, v41
	global_store_dwordx4 v[34:35], v[26:29], off
	s_nop 0
	s_waitcnt vmcnt(1)
	v_cvt_f32_ubyte3_e32 v31, v200
	v_cvt_f32_ubyte1_e32 v29, v200
	v_cvt_f32_ubyte0_e32 v28, v200
	v_cvt_f32_ubyte2_e32 v30, v200
	v_cvt_f32_ubyte1_e32 v33, v201
	v_cvt_f32_ubyte0_e32 v32, v201
	v_cvt_f32_ubyte3_e32 v37, v201
	v_cvt_f32_ubyte2_e32 v36, v201
	v_pk_mul_f32 v[26:27], v[28:29], s[10:11] op_sel_hi:[1,0]
	v_pk_mul_f32 v[28:29], v[30:31], s[10:11] op_sel_hi:[1,0]
	v_pk_mul_f32 v[30:31], v[32:33], s[10:11] op_sel_hi:[1,0]
	v_pk_mul_f32 v[32:33], v[36:37], s[10:11] op_sel_hi:[1,0]
	v_pk_mul_f32 v[22:23], v[22:23], v[26:27]
	v_pk_mul_f32 v[24:25], v[24:25], v[28:29]
	v_pk_mul_f32 v[26:27], v[18:19], v[30:31]
	v_pk_mul_f32 v[28:29], v[20:21], v[32:33]
	v_cvt_pk_bf16_f32 v18, v22, v23
	v_cvt_pk_bf16_f32 v19, v24, v25
	v_cvt_pk_bf16_f32 v20, v26, v27
	v_cvt_pk_bf16_f32 v21, v28, v29
	global_store_dwordx4 v[34:35], v[18:21], off offset:256
	s_nop 1
	v_lshl_add_u64 v[18:19], v[136:137], 0, s[44:45]
	v_lshl_add_u64 v[20:21], s[22:23], 0, v[18:19]
	v_lshl_add_u64 v[20:21], v[20:21], 0, v[134:135]
	global_load_dwordx2 v[22:23], v[20:21], off
	global_load_dwordx2 v[200:201], v[20:21], off offset:128
	v_lshl_add_u64 v[18:19], s[20:21], 0, v[18:19]
	v_lshl_add_u64 v[18:19], v[18:19], 0, v[138:139]
	s_waitcnt vmcnt(1)
	v_cvt_f32_ubyte1_e32 v25, v22
	v_cvt_f32_ubyte0_e32 v24, v22
	v_cvt_f32_ubyte3_e32 v27, v22
	v_cvt_f32_ubyte2_e32 v26, v22
	v_cvt_f32_ubyte1_e32 v29, v23
	v_cvt_f32_ubyte0_e32 v28, v23
	v_cvt_f32_ubyte3_e32 v31, v23
	v_cvt_f32_ubyte2_e32 v30, v23
	v_pk_mul_f32 v[22:23], v[24:25], s[10:11] op_sel_hi:[1,0]
	v_pk_mul_f32 v[24:25], v[26:27], s[10:11] op_sel_hi:[1,0]
	v_pk_mul_f32 v[26:27], v[28:29], s[10:11] op_sel_hi:[1,0]
	v_pk_mul_f32 v[28:29], v[30:31], s[10:11] op_sel_hi:[1,0]
	v_pk_mul_f32 v[14:15], v[14:15], v[22:23]
	v_pk_mul_f32 v[16:17], v[16:17], v[24:25]
	v_pk_mul_f32 v[22:23], v[10:11], v[26:27]
	v_pk_mul_f32 v[24:25], v[12:13], v[28:29]
	v_cvt_pk_bf16_f32 v10, v14, v15
	v_cvt_pk_bf16_f32 v11, v16, v17
	v_cvt_pk_bf16_f32 v12, v22, v23
	v_cvt_pk_bf16_f32 v13, v24, v25
	global_store_dwordx4 v[18:19], v[10:13], off
	s_nop 0
	s_waitcnt vmcnt(1)
	v_cvt_f32_ubyte3_e32 v15, v200
	v_cvt_f32_ubyte1_e32 v13, v200
	v_cvt_f32_ubyte0_e32 v12, v200
	v_cvt_f32_ubyte2_e32 v14, v200
	v_cvt_f32_ubyte1_e32 v17, v201
	v_cvt_f32_ubyte0_e32 v16, v201
	v_cvt_f32_ubyte3_e32 v21, v201
	v_cvt_f32_ubyte2_e32 v20, v201
	v_pk_mul_f32 v[10:11], v[12:13], s[10:11] op_sel_hi:[1,0]
	v_pk_mul_f32 v[12:13], v[14:15], s[10:11] op_sel_hi:[1,0]
	v_pk_mul_f32 v[14:15], v[16:17], s[10:11] op_sel_hi:[1,0]
	v_pk_mul_f32 v[16:17], v[20:21], s[10:11] op_sel_hi:[1,0]
	v_pk_mul_f32 v[6:7], v[6:7], v[10:11]
	v_pk_mul_f32 v[8:9], v[8:9], v[12:13]
	v_pk_mul_f32 v[10:11], v[2:3], v[14:15]
	v_pk_mul_f32 v[12:13], v[4:5], v[16:17]
	v_cvt_pk_bf16_f32 v2, v6, v7
	v_cvt_pk_bf16_f32 v3, v8, v9
	v_cvt_pk_bf16_f32 v4, v10, v11
	v_cvt_pk_bf16_f32 v5, v12, v13
	global_store_dwordx4 v[18:19], v[2:5], off offset:256
	s_andn2_b64 vcc, exec, s[4:5]
	s_mov_b64 s[4:5], -1
	s_cbranch_vccnz .LBB0_1271
	s_andn2_b64 vcc, exec, s[6:7]
	s_cbranch_vccnz .LBB0_1270
	s_barrier
	s_branch .LBB0_1270

; __device__ __forceinline__ float bflo(unsigned w) { return __uint_as_float(w << 16); }
; __device__ __forceinline__ float bfhi(unsigned w) { return __uint_as_float(w & 0xffff0000u); }
; __device__ __forceinline__ u32x4 pack8(f32x4 a, f32x4 b) { u32x4 w; w.x = pk2(a[0], a[1]); w.y = pk2(a[2], a[3]); w.z = pk2(b[0], b[1]); w.w = pk2(b[2], b[3]); return w; }
;     __device__ __forceinline__ void operator()(AccRef acc, const Unit& u, int wr, int wc, int fr, int fq) const {
;     ...
;             _Pragma("unroll") for (int bj = 0; bj < 2; ++bj) { const int col = col0 + bj * 128;
;                 const u32x2 gw = *(const u32x2*)(ZG8 + (size_t)row * 2048 + WHICH * 1024 + col);
;                 f32x4 v[2];
;                 _Pragma("unroll") for (int n = 0; n < 2; ++n) _Pragma("unroll") for (int i = 0; i < 4; ++i) v[n][i] = acc[ai][bj][m][n][i] * ((float)((gw[n] >> (8 * i)) & 255u) * (1.f / 255.f));
;                 if (WHICH == 0) *(u32x4*)(M1 + (size_t)row * 1024 + col) = pack8(v[0], v[1]);
;                 else { const u32x4 mw = *(const u32x4*)(M1 + (size_t)row * 1024 + col);
;                     _Pragma("unroll") for (int n = 0; n < 2; ++n) { v[n][0] += bflo(mw[2 * n]); v[n][1] += bfhi(mw[2 * n]); v[n][2] += bflo(mw[2 * n + 1]); v[n][3] += bfhi(mw[2 * n + 1]); }
;                     *(u32x4*)(MB + (size_t)row * 1024 + col) = pack8(v[0], v[1]); } }
.LBB0_1294:
	v_lshl_add_u32 v142, s54, 8, v147
	v_ashrrev_i32_e32 v143, 31, v142
	v_lshl_or_b32 v136, s52, 8, v148
	v_lshlrev_b64 v[138:139], 11, v[142:143]
	v_lshl_add_u64 v[134:135], s[22:23], 0, v[138:139]
	v_ashrrev_i32_e32 v137, 31, v136
	v_lshl_add_u64 v[158:159], v[134:135], 0, v[136:137]
	v_lshl_add_u64 v[154:155], s[20:21], 0, v[138:139]
	v_lshlrev_b64 v[134:135], 1, v[136:137]
	global_load_dwordx2 v[160:161], v[158:159], off offset:1024
	v_lshl_add_u64 v[162:163], v[154:155], 0, v[134:135]
	global_load_dwordx4 v[154:157], v[162:163], off
	global_load_dwordx2 v[200:201], v[158:159], off offset:1152
	global_load_dwordx4 v[204:207], v[162:163], off offset:256
	v_lshl_add_u64 v[164:165], s[36:37], 0, v[138:139]
	v_lshl_add_u64 v[164:165], v[164:165], 0, v[134:135]
	s_waitcnt vmcnt(3)
	v_cvt_f32_ubyte1_e32 v167, v160
	v_cvt_f32_ubyte0_e32 v166, v160
	v_cvt_f32_ubyte3_e32 v171, v160
	v_cvt_f32_ubyte2_e32 v170, v160
	v_cvt_f32_ubyte1_e32 v173, v161
	v_cvt_f32_ubyte0_e32 v172, v161
	v_cvt_f32_ubyte3_e32 v177, v161
	v_cvt_f32_ubyte2_e32 v176, v161
	s_waitcnt vmcnt(2)
	v_lshlrev_b32_e32 v168, 16, v154
	v_and_b32_e32 v169, 0xffff0000, v154
	v_lshlrev_b32_e32 v154, 16, v155
	v_and_b32_e32 v155, 0xffff0000, v155
	v_lshlrev_b32_e32 v174, 16, v156
	v_and_b32_e32 v175, 0xffff0000, v156
	v_lshlrev_b32_e32 v156, 16, v157
	v_and_b32_e32 v157, 0xffff0000, v157
	v_pk_mul_f32 v[160:161], v[166:167], s[10:11] op_sel_hi:[1,0]
	v_pk_mul_f32 v[166:167], v[170:171], s[10:11] op_sel_hi:[1,0]
	v_pk_mul_f32 v[170:171], v[172:173], s[10:11] op_sel_hi:[1,0]
	v_pk_mul_f32 v[172:173], v[176:177], s[10:11] op_sel_hi:[1,0]
	v_pk_fma_f32 v[126:127], v[126:127], v[160:161], v[168:169]
	v_pk_fma_f32 v[128:129], v[128:129], v[166:167], v[154:155]
	v_pk_fma_f32 v[154:155], v[122:123], v[170:171], v[174:175]
	v_pk_fma_f32 v[156:157], v[124:125], v[172:173], v[156:157]
	v_cvt_pk_bf16_f32 v122, v126, v127
	v_cvt_pk_bf16_f32 v123, v128, v129
	v_cvt_pk_bf16_f32 v124, v154, v155
	v_cvt_pk_bf16_f32 v125, v156, v157
	global_store_dwordx4 v[164:165], v[122:125], off
	s_nop 0
	s_nop 0
	s_nop 0
	s_waitcnt vmcnt(2)
	v_cvt_f32_ubyte1_e32 v129, v200
	v_cvt_f32_ubyte0_e32 v128, v200
	v_cvt_f32_ubyte3_e32 v157, v200
	v_cvt_f32_ubyte2_e32 v156, v200
	v_cvt_f32_ubyte1_e32 v159, v201
	v_cvt_f32_ubyte0_e32 v158, v201
	v_cvt_f32_ubyte3_e32 v163, v201
	v_cvt_f32_ubyte2_e32 v162, v201
	s_waitcnt vmcnt(1)
	v_lshlrev_b32_e32 v154, 16, v204
	v_and_b32_e32 v155, 0xffff0000, v204
	v_lshlrev_b32_e32 v122, 16, v205
	v_and_b32_e32 v123, 0xffff0000, v205
	v_lshlrev_b32_e32 v160, 16, v206
	v_and_b32_e32 v161, 0xffff0000, v206
	v_lshlrev_b32_e32 v124, 16, v207
	v_and_b32_e32 v125, 0xffff0000, v207
	v_pk_mul_f32 v[126:127], v[128:129], s[10:11] op_sel_hi:[1,0]
	v_pk_mul_f32 v[128:129], v[156:157], s[10:11] op_sel_hi:[1,0]
	v_pk_mul_f32 v[156:157], v[158:159], s[10:11] op_sel_hi:[1,0]
	v_pk_mul_f32 v[158:159], v[162:163], s[10:11] op_sel_hi:[1,0]
	v_pk_fma_f32 v[118:119], v[118:119], v[126:127], v[154:155]
	v_pk_fma_f32 v[120:121], v[120:121], v[128:129], v[122:123]
	v_pk_fma_f32 v[122:123], v[114:115], v[156:157], v[160:161]
	v_pk_fma_f32 v[124:125], v[116:117], v[158:159], v[124:125]
	v_cvt_pk_bf16_f32 v114, v118, v119
	v_cvt_pk_bf16_f32 v115, v120, v121
	v_cvt_pk_bf16_f32 v116, v122, v123
	v_cvt_pk_bf16_f32 v117, v124, v125
	global_store_dwordx4 v[164:165], v[114:117], off offset:256
	s_nop 1
	v_or_b32_e32 v114, 16, v142
	v_ashrrev_i32_e32 v115, 31, v114
	v_lshlrev_b64 v[118:119], 11, v[114:115]
	v_lshl_add_u64 v[114:115], s[22:23], 0, v[118:119]
	v_lshl_add_u64 v[120:121], v[114:115], 0, v[136:137]
	v_lshl_add_u64 v[114:115], s[20:21], 0, v[118:119]
	global_load_dwordx2 v[122:123], v[120:121], off offset:1024
	v_lshl_add_u64 v[124:125], v[114:115], 0, v[134:135]
	global_load_dwordx4 v[114:117], v[124:125], off
	global_load_dwordx2 v[200:201], v[120:121], off offset:1152
	global_load_dwordx4 v[204:207], v[124:125], off offset:256
	v_lshl_add_u64 v[118:119], s[36:37], 0, v[118:119]
	v_lshl_add_u64 v[118:119], v[118:119], 0, v[134:135]
	s_waitcnt vmcnt(3)
	v_cvt_f32_ubyte1_e32 v127, v122
	v_cvt_f32_ubyte0_e32 v126, v122
	v_cvt_f32_ubyte3_e32 v155, v122
	v_cvt_f32_ubyte2_e32 v154, v122
	v_cvt_f32_ubyte1_e32 v157, v123
	v_cvt_f32_ubyte0_e32 v156, v123
	v_cvt_f32_ubyte3_e32 v161, v123
	v_cvt_f32_ubyte2_e32 v160, v123
	s_waitcnt vmcnt(2)
	v_lshlrev_b32_e32 v128, 16, v114
	v_and_b32_e32 v129, 0xffff0000, v114
	v_lshlrev_b32_e32 v114, 16, v115
	v_and_b32_e32 v115, 0xffff0000, v115
	v_lshlrev_b32_e32 v158, 16, v116
	v_and_b32_e32 v159, 0xffff0000, v116
	v_lshlrev_b32_e32 v116, 16, v117
	v_and_b32_e32 v117, 0xffff0000, v117
	v_pk_mul_f32 v[122:123], v[126:127], s[10:11] op_sel_hi:[1,0]
	v_pk_mul_f32 v[126:127], v[154:155], s[10:11] op_sel_hi:[1,0]
	v_pk_mul_f32 v[154:155], v[156:157], s[10:11] op_sel_hi:[1,0]
	v_pk_mul_f32 v[156:157], v[160:161], s[10:11] op_sel_hi:[1,0]
	v_pk_fma_f32 v[110:111], v[110:111], v[122:123], v[128:129]
	v_pk_fma_f32 v[112:113], v[112:113], v[126:127], v[114:115]
	v_pk_fma_f32 v[114:115], v[106:107], v[154:155], v[158:159]
	v_pk_fma_f32 v[116:117], v[108:109], v[156:157], v[116:117]
	v_cvt_pk_bf16_f32 v106, v110, v111
	v_cvt_pk_bf16_f32 v107, v112, v113
	v_cvt_pk_bf16_f32 v108, v114, v115
	v_cvt_pk_bf16_f32 v109, v116, v117
	global_store_dwordx4 v[118:119], v[106:109], off
	s_nop 0
	s_nop 0
	s_nop 0
	s_waitcnt vmcnt(2)
	v_cvt_f32_ubyte1_e32 v113, v200
	v_cvt_f32_ubyte0_e32 v112, v200
	v_cvt_f32_ubyte3_e32 v117, v200
	v_cvt_f32_ubyte2_e32 v116, v200
	v_cvt_f32_ubyte1_e32 v121, v201
	v_cvt_f32_ubyte0_e32 v120, v201
	v_cvt_f32_ubyte3_e32 v125, v201
	v_cvt_f32_ubyte2_e32 v124, v201
	s_waitcnt vmcnt(1)
; __device__ __forceinline__ float bflo(unsigned w) { return __uint_as_float(w << 16); }
; __device__ __forceinline__ float bfhi(unsigned w) { return __uint_as_float(w & 0xffff0000u); }
; __device__ __forceinline__ u32x4 pack8(f32x4 a, f32x4 b) { u32x4 w; w.x = pk2(a[0], a[1]); w.y = pk2(a[2], a[3]); w.z = pk2(b[0], b[1]); w.w = pk2(b[2], b[3]); return w; }
;     __device__ __forceinline__ void operator()(AccRef acc, const Unit& u, int wr, int wc, int fr, int fq) const {
;     ...
;             _Pragma("unroll") for (int bj = 0; bj < 2; ++bj) { const int col = col0 + bj * 128;
;                 const u32x2 gw = *(const u32x2*)(ZG8 + (size_t)row * 2048 + WHICH * 1024 + col);
;                 f32x4 v[2];
;                 _Pragma("unroll") for (int n = 0; n < 2; ++n) _Pragma("unroll") for (int i = 0; i < 4; ++i) v[n][i] = acc[ai][bj][m][n][i] * ((float)((gw[n] >> (8 * i)) & 255u) * (1.f / 255.f));
;                 if (WHICH == 0) *(u32x4*)(M1 + (size_t)row * 1024 + col) = pack8(v[0], v[1]);
;                 else { const u32x4 mw = *(const u32x4*)(M1 + (size_t)row * 1024 + col);
;                     _Pragma("unroll") for (int n = 0; n < 2; ++n) { v[n][0] += bflo(mw[2 * n]); v[n][1] += bfhi(mw[2 * n]); v[n][2] += bflo(mw[2 * n + 1]); v[n][3] += bfhi(mw[2 * n + 1]); }
;                     *(u32x4*)(MB + (size_t)row * 1024 + col) = pack8(v[0], v[1]); } }
	v_lshlrev_b32_e32 v114, 16, v204
	v_and_b32_e32 v115, 0xffff0000, v204
	v_lshlrev_b32_e32 v106, 16, v205
	v_and_b32_e32 v107, 0xffff0000, v205
	v_lshlrev_b32_e32 v122, 16, v206
	v_and_b32_e32 v123, 0xffff0000, v206
	v_lshlrev_b32_e32 v108, 16, v207
	v_and_b32_e32 v109, 0xffff0000, v207
	v_pk_mul_f32 v[110:111], v[112:113], s[10:11] op_sel_hi:[1,0]
	v_pk_mul_f32 v[112:113], v[116:117], s[10:11] op_sel_hi:[1,0]
	v_pk_mul_f32 v[116:117], v[120:121], s[10:11] op_sel_hi:[1,0]
	v_pk_mul_f32 v[120:121], v[124:125], s[10:11] op_sel_hi:[1,0]
	v_pk_fma_f32 v[102:103], v[102:103], v[110:111], v[114:115]
	v_pk_fma_f32 v[104:105], v[104:105], v[112:113], v[106:107]
	v_pk_fma_f32 v[106:107], v[98:99], v[116:117], v[122:123]
	v_pk_fma_f32 v[108:109], v[100:101], v[120:121], v[108:109]
	v_cvt_pk_bf16_f32 v98, v102, v103
	v_cvt_pk_bf16_f32 v99, v104, v105
	v_cvt_pk_bf16_f32 v100, v106, v107
	v_cvt_pk_bf16_f32 v101, v108, v109
	global_store_dwordx4 v[118:119], v[98:101], off offset:256
	s_nop 1
	v_or_b32_e32 v98, 32, v142
	v_ashrrev_i32_e32 v99, 31, v98
	v_lshlrev_b64 v[102:103], 11, v[98:99]
	v_lshl_add_u64 v[98:99], s[22:23], 0, v[102:103]
	v_lshl_add_u64 v[104:105], v[98:99], 0, v[136:137]
	v_lshl_add_u64 v[98:99], s[20:21], 0, v[102:103]
	global_load_dwordx2 v[106:107], v[104:105], off offset:1024
	v_lshl_add_u64 v[108:109], v[98:99], 0, v[134:135]
	global_load_dwordx4 v[98:101], v[108:109], off
	global_load_dwordx2 v[200:201], v[104:105], off offset:1152
	global_load_dwordx4 v[204:207], v[108:109], off offset:256
	v_lshl_add_u64 v[102:103], s[36:37], 0, v[102:103]
	v_lshl_add_u64 v[102:103], v[102:103], 0, v[134:135]
	s_waitcnt vmcnt(3)
	v_cvt_f32_ubyte1_e32 v111, v106
	v_cvt_f32_ubyte0_e32 v110, v106
	v_cvt_f32_ubyte3_e32 v115, v106
	v_cvt_f32_ubyte2_e32 v114, v106
	v_cvt_f32_ubyte1_e32 v117, v107
	v_cvt_f32_ubyte0_e32 v116, v107
	v_cvt_f32_ubyte3_e32 v121, v107
	v_cvt_f32_ubyte2_e32 v120, v107
	s_waitcnt vmcnt(2)
	v_lshlrev_b32_e32 v112, 16, v98
	v_and_b32_e32 v113, 0xffff0000, v98
	v_lshlrev_b32_e32 v98, 16, v99
	v_and_b32_e32 v99, 0xffff0000, v99
	v_lshlrev_b32_e32 v118, 16, v100
	v_and_b32_e32 v119, 0xffff0000, v100
	v_lshlrev_b32_e32 v100, 16, v101
	v_and_b32_e32 v101, 0xffff0000, v101
	v_pk_mul_f32 v[106:107], v[110:111], s[10:11] op_sel_hi:[1,0]
	v_pk_mul_f32 v[110:111], v[114:115], s[10:11] op_sel_hi:[1,0]
	v_pk_mul_f32 v[114:115], v[116:117], s[10:11] op_sel_hi:[1,0]
	v_pk_mul_f32 v[116:117], v[120:121], s[10:11] op_sel_hi:[1,0]
	v_pk_fma_f32 v[94:95], v[94:95], v[106:107], v[112:113]
	v_pk_fma_f32 v[96:97], v[96:97], v[110:111], v[98:99]
	v_pk_fma_f32 v[98:99], v[90:91], v[114:115], v[118:119]
	v_pk_fma_f32 v[100:101], v[92:93], v[116:117], v[100:101]
	v_cvt_pk_bf16_f32 v90, v94, v95
	v_cvt_pk_bf16_f32 v91, v96, v97
	v_cvt_pk_bf16_f32 v92, v98, v99
	v_cvt_pk_bf16_f32 v93, v100, v101
	global_store_dwordx4 v[102:103], v[90:93], off
	s_nop 0
	s_nop 0
	s_nop 0
	s_waitcnt vmcnt(2)
	v_cvt_f32_ubyte1_e32 v97, v200
	v_cvt_f32_ubyte0_e32 v96, v200
	v_cvt_f32_ubyte3_e32 v101, v200
	v_cvt_f32_ubyte2_e32 v100, v200
	v_cvt_f32_ubyte1_e32 v105, v201
	v_cvt_f32_ubyte0_e32 v104, v201
	v_cvt_f32_ubyte3_e32 v109, v201
	v_cvt_f32_ubyte2_e32 v108, v201
	s_waitcnt vmcnt(1)
	v_lshlrev_b32_e32 v98, 16, v204
	v_and_b32_e32 v99, 0xffff0000, v204
	v_lshlrev_b32_e32 v90, 16, v205
	v_and_b32_e32 v91, 0xffff0000, v205
	v_lshlrev_b32_e32 v106, 16, v206
	v_and_b32_e32 v107, 0xffff0000, v206
	v_lshlrev_b32_e32 v92, 16, v207
	v_and_b32_e32 v93, 0xffff0000, v207
	v_pk_mul_f32 v[94:95], v[96:97], s[10:11] op_sel_hi:[1,0]
	v_pk_mul_f32 v[96:97], v[100:101], s[10:11] op_sel_hi:[1,0]
	v_pk_mul_f32 v[100:101], v[104:105], s[10:11] op_sel_hi:[1,0]
	v_pk_mul_f32 v[104:105], v[108:109], s[10:11] op_sel_hi:[1,0]
	v_pk_fma_f32 v[86:87], v[86:87], v[94:95], v[98:99]
	v_pk_fma_f32 v[88:89], v[88:89], v[96:97], v[90:91]
	v_pk_fma_f32 v[90:91], v[82:83], v[100:101], v[106:107]
	v_pk_fma_f32 v[92:93], v[84:85], v[104:105], v[92:93]
	v_cvt_pk_bf16_f32 v82, v86, v87
	v_cvt_pk_bf16_f32 v83, v88, v89
	v_cvt_pk_bf16_f32 v84, v90, v91
	v_cvt_pk_bf16_f32 v85, v92, v93
	global_store_dwordx4 v[102:103], v[82:85], off offset:256
	s_nop 1
	v_or_b32_e32 v82, 48, v142
	v_ashrrev_i32_e32 v83, 31, v82
	v_lshlrev_b64 v[86:87], 11, v[82:83]
	v_lshl_add_u64 v[82:83], s[22:23], 0, v[86:87]
	v_lshl_add_u64 v[88:89], v[82:83], 0, v[136:137]
	v_lshl_add_u64 v[82:83], s[20:21], 0, v[86:87]
	global_load_dwordx2 v[90:91], v[88:89], off offset:1024
	v_lshl_add_u64 v[92:93], v[82:83], 0, v[134:135]
	global_load_dwordx4 v[82:85], v[92:93], off
	global_load_dwordx2 v[200:201], v[88:89], off offset:1152
	global_load_dwordx4 v[204:207], v[92:93], off offset:256
	v_lshl_add_u64 v[86:87], s[36:37], 0, v[86:87]
	v_lshl_add_u64 v[86:87], v[86:87], 0, v[134:135]
	s_waitcnt vmcnt(3)
	v_cvt_f32_ubyte1_e32 v95, v90
	v_cvt_f32_ubyte0_e32 v94, v90
	v_cvt_f32_ubyte3_e32 v99, v90
	v_cvt_f32_ubyte2_e32 v98, v90
	v_cvt_f32_ubyte1_e32 v101, v91
	v_cvt_f32_ubyte0_e32 v100, v91
	v_cvt_f32_ubyte3_e32 v105, v91
	v_cvt_f32_ubyte2_e32 v104, v91
	s_waitcnt vmcnt(2)
	v_lshlrev_b32_e32 v96, 16, v82
	v_and_b32_e32 v97, 0xffff0000, v82
	v_lshlrev_b32_e32 v82, 16, v83
	v_and_b32_e32 v83, 0xffff0000, v83
	v_lshlrev_b32_e32 v102, 16, v84
	v_and_b32_e32 v103, 0xffff0000, v84
	v_lshlrev_b32_e32 v84, 16, v85
	v_and_b32_e32 v85, 0xffff0000, v85
	v_pk_mul_f32 v[90:91], v[94:95], s[10:11] op_sel_hi:[1,0]
	v_pk_mul_f32 v[94:95], v[98:99], s[10:11] op_sel_hi:[1,0]
	v_pk_mul_f32 v[98:99], v[100:101], s[10:11] op_sel_hi:[1,0]
	v_pk_mul_f32 v[100:101], v[104:105], s[10:11] op_sel_hi:[1,0]
	v_pk_fma_f32 v[78:79], v[78:79], v[90:91], v[96:97]
	v_pk_fma_f32 v[80:81], v[80:81], v[94:95], v[82:83]
	v_pk_fma_f32 v[82:83], v[74:75], v[98:99], v[102:103]
	v_pk_fma_f32 v[84:85], v[76:77], v[100:101], v[84:85]
	v_cvt_pk_bf16_f32 v74, v78, v79
	v_cvt_pk_bf16_f32 v75, v80, v81
	v_cvt_pk_bf16_f32 v76, v82, v83
	v_cvt_pk_bf16_f32 v77, v84, v85
	global_store_dwordx4 v[86:87], v[74:77], off
	s_nop 0
	s_nop 0
	s_nop 0
	s_waitcnt vmcnt(2)
; __device__ __forceinline__ float bflo(unsigned w) { return __uint_as_float(w << 16); }
; __device__ __forceinline__ float bfhi(unsigned w) { return __uint_as_float(w & 0xffff0000u); }
; __device__ __forceinline__ u32x4 pack8(f32x4 a, f32x4 b) { u32x4 w; w.x = pk2(a[0], a[1]); w.y = pk2(a[2], a[3]); w.z = pk2(b[0], b[1]); w.w = pk2(b[2], b[3]); return w; }
;     __device__ __forceinline__ void operator()(AccRef acc, const Unit& u, int wr, int wc, int fr, int fq) const {
;     ...
;             _Pragma("unroll") for (int bj = 0; bj < 2; ++bj) { const int col = col0 + bj * 128;
;                 const u32x2 gw = *(const u32x2*)(ZG8 + (size_t)row * 2048 + WHICH * 1024 + col);
;                 f32x4 v[2];
;                 _Pragma("unroll") for (int n = 0; n < 2; ++n) _Pragma("unroll") for (int i = 0; i < 4; ++i) v[n][i] = acc[ai][bj][m][n][i] * ((float)((gw[n] >> (8 * i)) & 255u) * (1.f / 255.f));
;                 if (WHICH == 0) *(u32x4*)(M1 + (size_t)row * 1024 + col) = pack8(v[0], v[1]);
;                 else { const u32x4 mw = *(const u32x4*)(M1 + (size_t)row * 1024 + col);
;                     _Pragma("unroll") for (int n = 0; n < 2; ++n) { v[n][0] += bflo(mw[2 * n]); v[n][1] += bfhi(mw[2 * n]); v[n][2] += bflo(mw[2 * n + 1]); v[n][3] += bfhi(mw[2 * n + 1]); }
;                     *(u32x4*)(MB + (size_t)row * 1024 + col) = pack8(v[0], v[1]); } }
	v_cvt_f32_ubyte1_e32 v81, v200
	v_cvt_f32_ubyte0_e32 v80, v200
	v_cvt_f32_ubyte3_e32 v85, v200
	v_cvt_f32_ubyte2_e32 v84, v200
	v_cvt_f32_ubyte1_e32 v89, v201
	v_cvt_f32_ubyte0_e32 v88, v201
	v_cvt_f32_ubyte3_e32 v93, v201
	v_cvt_f32_ubyte2_e32 v92, v201
	s_waitcnt vmcnt(1)
	v_lshlrev_b32_e32 v82, 16, v204
	v_and_b32_e32 v83, 0xffff0000, v204
	v_lshlrev_b32_e32 v74, 16, v205
	v_and_b32_e32 v75, 0xffff0000, v205
	v_lshlrev_b32_e32 v90, 16, v206
	v_and_b32_e32 v91, 0xffff0000, v206
	v_lshlrev_b32_e32 v76, 16, v207
	v_and_b32_e32 v77, 0xffff0000, v207
	v_pk_mul_f32 v[78:79], v[80:81], s[10:11] op_sel_hi:[1,0]
	v_pk_mul_f32 v[80:81], v[84:85], s[10:11] op_sel_hi:[1,0]
	v_pk_mul_f32 v[84:85], v[88:89], s[10:11] op_sel_hi:[1,0]
	v_pk_mul_f32 v[88:89], v[92:93], s[10:11] op_sel_hi:[1,0]
	v_pk_fma_f32 v[70:71], v[70:71], v[78:79], v[82:83]
	v_pk_fma_f32 v[72:73], v[72:73], v[80:81], v[74:75]
	v_pk_fma_f32 v[74:75], v[66:67], v[84:85], v[90:91]
	v_pk_fma_f32 v[76:77], v[68:69], v[88:89], v[76:77]
	v_cvt_pk_bf16_f32 v66, v70, v71
	v_cvt_pk_bf16_f32 v67, v72, v73
	v_cvt_pk_bf16_f32 v68, v74, v75
	v_cvt_pk_bf16_f32 v69, v76, v77
	global_store_dwordx4 v[86:87], v[66:69], off offset:256
	v_lshl_add_u64 v[70:71], v[138:139], 0, s[0:1]
	s_nop 0
	v_lshl_add_u64 v[66:67], s[22:23], 0, v[70:71]
	v_lshl_add_u64 v[72:73], v[66:67], 0, v[136:137]
	v_lshl_add_u64 v[66:67], s[20:21], 0, v[70:71]
	global_load_dwordx2 v[74:75], v[72:73], off offset:1024
	v_lshl_add_u64 v[76:77], v[66:67], 0, v[134:135]
	global_load_dwordx4 v[66:69], v[76:77], off
	global_load_dwordx2 v[200:201], v[72:73], off offset:1152
	global_load_dwordx4 v[204:207], v[76:77], off offset:256
	v_lshl_add_u64 v[70:71], s[36:37], 0, v[70:71]
	v_lshl_add_u64 v[70:71], v[70:71], 0, v[134:135]
	s_waitcnt vmcnt(3)
	v_cvt_f32_ubyte1_e32 v79, v74
	v_cvt_f32_ubyte0_e32 v78, v74
	v_cvt_f32_ubyte3_e32 v83, v74
	v_cvt_f32_ubyte2_e32 v82, v74
	v_cvt_f32_ubyte1_e32 v85, v75
	v_cvt_f32_ubyte0_e32 v84, v75
	v_cvt_f32_ubyte3_e32 v89, v75
	v_cvt_f32_ubyte2_e32 v88, v75
	s_waitcnt vmcnt(2)
	v_lshlrev_b32_e32 v80, 16, v66
	v_and_b32_e32 v81, 0xffff0000, v66
	v_lshlrev_b32_e32 v66, 16, v67
	v_and_b32_e32 v67, 0xffff0000, v67
	v_lshlrev_b32_e32 v86, 16, v68
	v_and_b32_e32 v87, 0xffff0000, v68
	v_lshlrev_b32_e32 v68, 16, v69
	v_and_b32_e32 v69, 0xffff0000, v69
	v_pk_mul_f32 v[74:75], v[78:79], s[10:11] op_sel_hi:[1,0]
	v_pk_mul_f32 v[78:79], v[82:83], s[10:11] op_sel_hi:[1,0]
	v_pk_mul_f32 v[82:83], v[84:85], s[10:11] op_sel_hi:[1,0]
	v_pk_mul_f32 v[84:85], v[88:89], s[10:11] op_sel_hi:[1,0]
	v_pk_fma_f32 v[62:63], v[62:63], v[74:75], v[80:81]
	v_pk_fma_f32 v[64:65], v[64:65], v[78:79], v[66:67]
	v_pk_fma_f32 v[66:67], v[58:59], v[82:83], v[86:87]
	v_pk_fma_f32 v[68:69], v[60:61], v[84:85], v[68:69]
	v_cvt_pk_bf16_f32 v58, v62, v63
	v_cvt_pk_bf16_f32 v59, v64, v65
	v_cvt_pk_bf16_f32 v60, v66, v67
	v_cvt_pk_bf16_f32 v61, v68, v69
	global_store_dwordx4 v[70:71], v[58:61], off
	s_nop 0
	s_nop 0
	s_nop 0
	s_waitcnt vmcnt(2)
	v_cvt_f32_ubyte1_e32 v65, v200
	v_cvt_f32_ubyte0_e32 v64, v200
	v_cvt_f32_ubyte3_e32 v69, v200
	v_cvt_f32_ubyte2_e32 v68, v200
	v_cvt_f32_ubyte1_e32 v73, v201
	v_cvt_f32_ubyte0_e32 v72, v201
	v_cvt_f32_ubyte3_e32 v77, v201
	v_cvt_f32_ubyte2_e32 v76, v201
	s_waitcnt vmcnt(1)
	v_lshlrev_b32_e32 v66, 16, v204
	v_and_b32_e32 v67, 0xffff0000, v204
	v_lshlrev_b32_e32 v58, 16, v205
	v_and_b32_e32 v59, 0xffff0000, v205
	v_lshlrev_b32_e32 v74, 16, v206
	v_and_b32_e32 v75, 0xffff0000, v206
	v_lshlrev_b32_e32 v60, 16, v207
	v_and_b32_e32 v61, 0xffff0000, v207
	v_pk_mul_f32 v[62:63], v[64:65], s[10:11] op_sel_hi:[1,0]
	v_pk_mul_f32 v[64:65], v[68:69], s[10:11] op_sel_hi:[1,0]
	v_pk_mul_f32 v[68:69], v[72:73], s[10:11] op_sel_hi:[1,0]
	v_pk_mul_f32 v[72:73], v[76:77], s[10:11] op_sel_hi:[1,0]
	v_pk_fma_f32 v[54:55], v[54:55], v[62:63], v[66:67]
	v_pk_fma_f32 v[56:57], v[56:57], v[64:65], v[58:59]
	v_pk_fma_f32 v[58:59], v[50:51], v[68:69], v[74:75]
	v_pk_fma_f32 v[60:61], v[52:53], v[72:73], v[60:61]
	v_cvt_pk_bf16_f32 v50, v54, v55
	v_cvt_pk_bf16_f32 v51, v56, v57
	v_cvt_pk_bf16_f32 v52, v58, v59
	v_cvt_pk_bf16_f32 v53, v60, v61
	global_store_dwordx4 v[70:71], v[50:53], off offset:256
	v_lshl_add_u64 v[54:55], v[138:139], 0, s[12:13]
	s_nop 0
	v_lshl_add_u64 v[50:51], s[22:23], 0, v[54:55]
	v_lshl_add_u64 v[56:57], v[50:51], 0, v[136:137]
	v_lshl_add_u64 v[50:51], s[20:21], 0, v[54:55]
	global_load_dwordx2 v[58:59], v[56:57], off offset:1024
	v_lshl_add_u64 v[60:61], v[50:51], 0, v[134:135]
	global_load_dwordx4 v[50:53], v[60:61], off
	global_load_dwordx2 v[200:201], v[56:57], off offset:1152
	global_load_dwordx4 v[204:207], v[60:61], off offset:256
	v_lshl_add_u64 v[54:55], s[36:37], 0, v[54:55]
	v_lshl_add_u64 v[54:55], v[54:55], 0, v[134:135]
	s_waitcnt vmcnt(3)
	v_cvt_f32_ubyte1_e32 v63, v58
	v_cvt_f32_ubyte0_e32 v62, v58
	v_cvt_f32_ubyte3_e32 v67, v58
	v_cvt_f32_ubyte2_e32 v66, v58
	v_cvt_f32_ubyte1_e32 v69, v59
	v_cvt_f32_ubyte0_e32 v68, v59
	v_cvt_f32_ubyte3_e32 v73, v59
	v_cvt_f32_ubyte2_e32 v72, v59
	s_waitcnt vmcnt(2)
	v_lshlrev_b32_e32 v64, 16, v50
	v_and_b32_e32 v65, 0xffff0000, v50
	v_lshlrev_b32_e32 v50, 16, v51
	v_and_b32_e32 v51, 0xffff0000, v51
	v_lshlrev_b32_e32 v70, 16, v52
	v_and_b32_e32 v71, 0xffff0000, v52
	v_lshlrev_b32_e32 v52, 16, v53
	v_and_b32_e32 v53, 0xffff0000, v53
	v_pk_mul_f32 v[58:59], v[62:63], s[10:11] op_sel_hi:[1,0]
	v_pk_mul_f32 v[62:63], v[66:67], s[10:11] op_sel_hi:[1,0]
	v_pk_mul_f32 v[66:67], v[68:69], s[10:11] op_sel_hi:[1,0]
	v_pk_mul_f32 v[68:69], v[72:73], s[10:11] op_sel_hi:[1,0]
	v_pk_fma_f32 v[46:47], v[46:47], v[58:59], v[64:65]
	v_pk_fma_f32 v[48:49], v[48:49], v[62:63], v[50:51]
	v_pk_fma_f32 v[50:51], v[42:43], v[66:67], v[70:71]
	v_pk_fma_f32 v[52:53], v[44:45], v[68:69], v[52:53]
	v_cvt_pk_bf16_f32 v42, v46, v47
	v_cvt_pk_bf16_f32 v43, v48, v49
	v_cvt_pk_bf16_f32 v44, v50, v51
	v_cvt_pk_bf16_f32 v45, v52, v53
	global_store_dwordx4 v[54:55], v[42:45], off
	s_nop 0
	s_nop 0
	s_nop 0
	s_waitcnt vmcnt(2)
; __device__ __forceinline__ float bflo(unsigned w) { return __uint_as_float(w << 16); }
; __device__ __forceinline__ float bfhi(unsigned w) { return __uint_as_float(w & 0xffff0000u); }
; __device__ __forceinline__ u32x4 pack8(f32x4 a, f32x4 b) { u32x4 w; w.x = pk2(a[0], a[1]); w.y = pk2(a[2], a[3]); w.z = pk2(b[0], b[1]); w.w = pk2(b[2], b[3]); return w; }
;     __device__ __forceinline__ void operator()(AccRef acc, const Unit& u, int wr, int wc, int fr, int fq) const {
;     ...
;             _Pragma("unroll") for (int bj = 0; bj < 2; ++bj) { const int col = col0 + bj * 128;
;                 const u32x2 gw = *(const u32x2*)(ZG8 + (size_t)row * 2048 + WHICH * 1024 + col);
;                 f32x4 v[2];
;                 _Pragma("unroll") for (int n = 0; n < 2; ++n) _Pragma("unroll") for (int i = 0; i < 4; ++i) v[n][i] = acc[ai][bj][m][n][i] * ((float)((gw[n] >> (8 * i)) & 255u) * (1.f / 255.f));
;                 if (WHICH == 0) *(u32x4*)(M1 + (size_t)row * 1024 + col) = pack8(v[0], v[1]);
;                 else { const u32x4 mw = *(const u32x4*)(M1 + (size_t)row * 1024 + col);
;                     _Pragma("unroll") for (int n = 0; n < 2; ++n) { v[n][0] += bflo(mw[2 * n]); v[n][1] += bfhi(mw[2 * n]); v[n][2] += bflo(mw[2 * n + 1]); v[n][3] += bfhi(mw[2 * n + 1]); }
;                     *(u32x4*)(MB + (size_t)row * 1024 + col) = pack8(v[0], v[1]); } }
	v_cvt_f32_ubyte1_e32 v49, v200
	v_cvt_f32_ubyte0_e32 v48, v200
	v_cvt_f32_ubyte3_e32 v53, v200
	v_cvt_f32_ubyte2_e32 v52, v200
	v_cvt_f32_ubyte1_e32 v57, v201
	v_cvt_f32_ubyte0_e32 v56, v201
	v_cvt_f32_ubyte3_e32 v61, v201
	v_cvt_f32_ubyte2_e32 v60, v201
	s_waitcnt vmcnt(1)
	v_lshlrev_b32_e32 v50, 16, v204
	v_and_b32_e32 v51, 0xffff0000, v204
	v_lshlrev_b32_e32 v42, 16, v205
	v_and_b32_e32 v43, 0xffff0000, v205
	v_lshlrev_b32_e32 v58, 16, v206
	v_and_b32_e32 v59, 0xffff0000, v206
	v_lshlrev_b32_e32 v44, 16, v207
	v_and_b32_e32 v45, 0xffff0000, v207
	v_pk_mul_f32 v[46:47], v[48:49], s[10:11] op_sel_hi:[1,0]
	v_pk_mul_f32 v[48:49], v[52:53], s[10:11] op_sel_hi:[1,0]
	v_pk_mul_f32 v[52:53], v[56:57], s[10:11] op_sel_hi:[1,0]
	v_pk_mul_f32 v[56:57], v[60:61], s[10:11] op_sel_hi:[1,0]
	v_pk_fma_f32 v[38:39], v[38:39], v[46:47], v[50:51]
	v_pk_fma_f32 v[40:41], v[40:41], v[48:49], v[42:43]
	v_pk_fma_f32 v[42:43], v[34:35], v[52:53], v[58:59]
	v_pk_fma_f32 v[44:45], v[36:37], v[56:57], v[44:45]
	v_cvt_pk_bf16_f32 v34, v38, v39
	v_cvt_pk_bf16_f32 v35, v40, v41
	v_cvt_pk_bf16_f32 v36, v42, v43
	v_cvt_pk_bf16_f32 v37, v44, v45
	global_store_dwordx4 v[54:55], v[34:37], off offset:256
	v_lshl_add_u64 v[38:39], v[138:139], 0, s[38:39]
	s_nop 0
	v_lshl_add_u64 v[34:35], s[22:23], 0, v[38:39]
	v_lshl_add_u64 v[40:41], v[34:35], 0, v[136:137]
	v_lshl_add_u64 v[34:35], s[20:21], 0, v[38:39]
	global_load_dwordx2 v[42:43], v[40:41], off offset:1024
	v_lshl_add_u64 v[44:45], v[34:35], 0, v[134:135]
	global_load_dwordx4 v[34:37], v[44:45], off
	global_load_dwordx2 v[200:201], v[40:41], off offset:1152
	global_load_dwordx4 v[204:207], v[44:45], off offset:256
	v_lshl_add_u64 v[38:39], s[36:37], 0, v[38:39]
	v_lshl_add_u64 v[38:39], v[38:39], 0, v[134:135]
	s_waitcnt vmcnt(3)
	v_cvt_f32_ubyte1_e32 v47, v42
	v_cvt_f32_ubyte0_e32 v46, v42
	v_cvt_f32_ubyte3_e32 v51, v42
	v_cvt_f32_ubyte2_e32 v50, v42
	v_cvt_f32_ubyte1_e32 v53, v43
	v_cvt_f32_ubyte0_e32 v52, v43
	v_cvt_f32_ubyte3_e32 v57, v43
	v_cvt_f32_ubyte2_e32 v56, v43
	s_waitcnt vmcnt(2)
	v_lshlrev_b32_e32 v48, 16, v34
	v_and_b32_e32 v49, 0xffff0000, v34
	v_lshlrev_b32_e32 v34, 16, v35
	v_and_b32_e32 v35, 0xffff0000, v35
	v_lshlrev_b32_e32 v54, 16, v36
	v_and_b32_e32 v55, 0xffff0000, v36
	v_lshlrev_b32_e32 v36, 16, v37
	v_and_b32_e32 v37, 0xffff0000, v37
	v_pk_mul_f32 v[42:43], v[46:47], s[10:11] op_sel_hi:[1,0]
	v_pk_mul_f32 v[46:47], v[50:51], s[10:11] op_sel_hi:[1,0]
	v_pk_mul_f32 v[50:51], v[52:53], s[10:11] op_sel_hi:[1,0]
	v_pk_mul_f32 v[52:53], v[56:57], s[10:11] op_sel_hi:[1,0]
	v_pk_fma_f32 v[30:31], v[30:31], v[42:43], v[48:49]
	v_pk_fma_f32 v[32:33], v[32:33], v[46:47], v[34:35]
	v_pk_fma_f32 v[34:35], v[26:27], v[50:51], v[54:55]
	v_pk_fma_f32 v[36:37], v[28:29], v[52:53], v[36:37]
	v_cvt_pk_bf16_f32 v26, v30, v31
	v_cvt_pk_bf16_f32 v27, v32, v33
	v_cvt_pk_bf16_f32 v28, v34, v35
	v_cvt_pk_bf16_f32 v29, v36, v37
	global_store_dwordx4 v[38:39], v[26:29], off
	s_nop 0
	s_nop 0
	s_nop 0
	s_waitcnt vmcnt(2)
	v_cvt_f32_ubyte1_e32 v33, v200
	v_cvt_f32_ubyte0_e32 v32, v200
	v_cvt_f32_ubyte3_e32 v37, v200
	v_cvt_f32_ubyte2_e32 v36, v200
	v_cvt_f32_ubyte1_e32 v41, v201
	v_cvt_f32_ubyte0_e32 v40, v201
	v_cvt_f32_ubyte3_e32 v45, v201
	v_cvt_f32_ubyte2_e32 v44, v201
	s_waitcnt vmcnt(1)
; __device__ __forceinline__ float bflo(unsigned w) { return __uint_as_float(w << 16); }
; __device__ __forceinline__ float bfhi(unsigned w) { return __uint_as_float(w & 0xffff0000u); }
; __device__ __forceinline__ u32x4 pack8(f32x4 a, f32x4 b) { u32x4 w; w.x = pk2(a[0], a[1]); w.y = pk2(a[2], a[3]); w.z = pk2(b[0], b[1]); w.w = pk2(b[2], b[3]); return w; }
;     __device__ __forceinline__ void operator()(AccRef acc, const Unit& u, int wr, int wc, int fr, int fq) const {
;     ...
;             _Pragma("unroll") for (int bj = 0; bj < 2; ++bj) { const int col = col0 + bj * 128;
;                 const u32x2 gw = *(const u32x2*)(ZG8 + (size_t)row * 2048 + WHICH * 1024 + col);
;                 f32x4 v[2];
;                 _Pragma("unroll") for (int n = 0; n < 2; ++n) _Pragma("unroll") for (int i = 0; i < 4; ++i) v[n][i] = acc[ai][bj][m][n][i] * ((float)((gw[n] >> (8 * i)) & 255u) * (1.f / 255.f));
;                 if (WHICH == 0) *(u32x4*)(M1 + (size_t)row * 1024 + col) = pack8(v[0], v[1]);
;                 else { const u32x4 mw = *(const u32x4*)(M1 + (size_t)row * 1024 + col);
;                     _Pragma("unroll") for (int n = 0; n < 2; ++n) { v[n][0] += bflo(mw[2 * n]); v[n][1] += bfhi(mw[2 * n]); v[n][2] += bflo(mw[2 * n + 1]); v[n][3] += bfhi(mw[2 * n + 1]); }
;                     *(u32x4*)(MB + (size_t)row * 1024 + col) = pack8(v[0], v[1]); } }
	v_lshlrev_b32_e32 v34, 16, v204
	v_and_b32_e32 v35, 0xffff0000, v204
	v_lshlrev_b32_e32 v26, 16, v205
	v_and_b32_e32 v27, 0xffff0000, v205
	v_lshlrev_b32_e32 v42, 16, v206
	v_and_b32_e32 v43, 0xffff0000, v206
	v_lshlrev_b32_e32 v28, 16, v207
	v_and_b32_e32 v29, 0xffff0000, v207
	v_pk_mul_f32 v[30:31], v[32:33], s[10:11] op_sel_hi:[1,0]
	v_pk_mul_f32 v[32:33], v[36:37], s[10:11] op_sel_hi:[1,0]
	v_pk_mul_f32 v[36:37], v[40:41], s[10:11] op_sel_hi:[1,0]
	v_pk_mul_f32 v[40:41], v[44:45], s[10:11] op_sel_hi:[1,0]
	v_pk_fma_f32 v[22:23], v[22:23], v[30:31], v[34:35]
	v_pk_fma_f32 v[24:25], v[24:25], v[32:33], v[26:27]
	v_pk_fma_f32 v[26:27], v[18:19], v[36:37], v[42:43]
	v_pk_fma_f32 v[28:29], v[20:21], v[40:41], v[28:29]
	v_cvt_pk_bf16_f32 v18, v22, v23
	v_cvt_pk_bf16_f32 v19, v24, v25
	v_cvt_pk_bf16_f32 v20, v26, v27
	v_cvt_pk_bf16_f32 v21, v28, v29
	global_store_dwordx4 v[38:39], v[18:21], off offset:256
	v_lshl_add_u64 v[22:23], v[138:139], 0, s[42:43]
	s_nop 0
	v_lshl_add_u64 v[18:19], s[22:23], 0, v[22:23]
	v_lshl_add_u64 v[24:25], v[18:19], 0, v[136:137]
	v_lshl_add_u64 v[18:19], s[20:21], 0, v[22:23]
	global_load_dwordx2 v[26:27], v[24:25], off offset:1024
	v_lshl_add_u64 v[28:29], v[18:19], 0, v[134:135]
	global_load_dwordx4 v[18:21], v[28:29], off
	global_load_dwordx2 v[200:201], v[24:25], off offset:1152
	global_load_dwordx4 v[204:207], v[28:29], off offset:256
	v_lshl_add_u64 v[22:23], s[36:37], 0, v[22:23]
	v_lshl_add_u64 v[22:23], v[22:23], 0, v[134:135]
	s_waitcnt vmcnt(3)
	v_cvt_f32_ubyte1_e32 v31, v26
	v_cvt_f32_ubyte0_e32 v30, v26
	v_cvt_f32_ubyte3_e32 v35, v26
	v_cvt_f32_ubyte2_e32 v34, v26
	v_cvt_f32_ubyte1_e32 v37, v27
	v_cvt_f32_ubyte0_e32 v36, v27
	v_cvt_f32_ubyte3_e32 v41, v27
	v_cvt_f32_ubyte2_e32 v40, v27
	s_waitcnt vmcnt(2)
	v_lshlrev_b32_e32 v32, 16, v18
	v_and_b32_e32 v33, 0xffff0000, v18
	v_lshlrev_b32_e32 v18, 16, v19
	v_and_b32_e32 v19, 0xffff0000, v19
	v_lshlrev_b32_e32 v38, 16, v20
	v_and_b32_e32 v39, 0xffff0000, v20
	v_lshlrev_b32_e32 v20, 16, v21
	v_and_b32_e32 v21, 0xffff0000, v21
	v_pk_mul_f32 v[26:27], v[30:31], s[10:11] op_sel_hi:[1,0]
	v_pk_mul_f32 v[30:31], v[34:35], s[10:11] op_sel_hi:[1,0]
	v_pk_mul_f32 v[34:35], v[36:37], s[10:11] op_sel_hi:[1,0]
	v_pk_mul_f32 v[36:37], v[40:41], s[10:11] op_sel_hi:[1,0]
	v_pk_fma_f32 v[14:15], v[14:15], v[26:27], v[32:33]
	v_pk_fma_f32 v[16:17], v[16:17], v[30:31], v[18:19]
	v_pk_fma_f32 v[18:19], v[10:11], v[34:35], v[38:39]
	v_pk_fma_f32 v[20:21], v[12:13], v[36:37], v[20:21]
	v_cvt_pk_bf16_f32 v10, v14, v15
	v_cvt_pk_bf16_f32 v11, v16, v17
	v_cvt_pk_bf16_f32 v12, v18, v19
	v_cvt_pk_bf16_f32 v13, v20, v21
	global_store_dwordx4 v[22:23], v[10:13], off
	s_nop 0
	s_nop 0
	s_nop 0
	s_waitcnt vmcnt(2)
	v_cvt_f32_ubyte1_e32 v17, v200
	v_cvt_f32_ubyte0_e32 v16, v200
	v_cvt_f32_ubyte3_e32 v21, v200
	v_cvt_f32_ubyte2_e32 v20, v200
	v_cvt_f32_ubyte1_e32 v25, v201
	v_cvt_f32_ubyte0_e32 v24, v201
	v_cvt_f32_ubyte3_e32 v29, v201
	v_cvt_f32_ubyte2_e32 v28, v201
	s_waitcnt vmcnt(1)
	v_lshlrev_b32_e32 v18, 16, v204
	v_and_b32_e32 v19, 0xffff0000, v204
	v_lshlrev_b32_e32 v10, 16, v205
	v_and_b32_e32 v11, 0xffff0000, v205
	v_lshlrev_b32_e32 v26, 16, v206
	v_and_b32_e32 v27, 0xffff0000, v206
	v_lshlrev_b32_e32 v12, 16, v207
	v_and_b32_e32 v13, 0xffff0000, v207
	v_pk_mul_f32 v[14:15], v[16:17], s[10:11] op_sel_hi:[1,0]
	v_pk_mul_f32 v[16:17], v[20:21], s[10:11] op_sel_hi:[1,0]
	v_pk_mul_f32 v[20:21], v[24:25], s[10:11] op_sel_hi:[1,0]
	v_pk_mul_f32 v[24:25], v[28:29], s[10:11] op_sel_hi:[1,0]
	v_pk_fma_f32 v[6:7], v[6:7], v[14:15], v[18:19]
	v_pk_fma_f32 v[8:9], v[8:9], v[16:17], v[10:11]
	v_pk_fma_f32 v[10:11], v[2:3], v[20:21], v[26:27]
	v_pk_fma_f32 v[12:13], v[4:5], v[24:25], v[12:13]
	v_cvt_pk_bf16_f32 v2, v6, v7
	v_cvt_pk_bf16_f32 v3, v8, v9
	v_cvt_pk_bf16_f32 v4, v10, v11
	v_cvt_pk_bf16_f32 v5, v12, v13
	global_store_dwordx4 v[22:23], v[2:5], off offset:256
	s_andn2_b64 vcc, exec, s[4:5]
	s_mov_b64 s[4:5], -1
	s_cbranch_vccnz .LBB0_1287
	s_andn2_b64 vcc, exec, s[6:7]
	s_cbranch_vccnz .LBB0_1286
	s_barrier
	s_branch .LBB0_1286
